# grid-barrier spin loops: s_sleep 1 -> s_sleep 0 (on top of v47)
# speedup vs baseline: 1.0052x; 1.0028x over previous
; DI unsigned xb_ld(unsigned* p)              { return __hip_atomic_load(p, __ATOMIC_RELAXED, __HIP_MEMORY_SCOPE_AGENT); }
; DI void xcd_barrier_complete(unsigned* bar, unsigned x, unsigned& nloc, unsigned& nx) {
;     ...
;   for (;;) {
;     sum = 0u; cnt = 0u; mine = 0u;
; #pragma unroll
;     for (unsigned j = 0; j < 16; ++j) { const unsigned c = xb_ld(&bar[XB_XCNT(j)]); sum += c; cnt += (c > 0u) ? 1u : 0u; mine = (j == x) ? c : mine; }
;     if (sum == G) break;
;     __builtin_amdgcn_s_sleep(1);
;     if ((++sp & 255u) == 0u) { if (xb_ld(&bar[XB_TMO])) break; if (sp > XB_SPIN_CAP) { atomicAdd(&bar[XB_TMO], 1u); break; } }
;   }
.LBB0_276:
	v_readlane_b32 s4, v254, 34
	v_readlane_b32 s5, v254, 35
	s_mov_b64 s[6:7], -1
	s_waitcnt lgkmcnt(0)
	s_nop 2
	global_load_dword v0, v177, s[4:5] sc1
	v_readlane_b32 s4, v254, 36
	v_readlane_b32 s5, v254, 37
	s_nop 4
	global_load_dword v1, v177, s[4:5] sc1
	v_readlane_b32 s4, v254, 38
	v_readlane_b32 s5, v254, 39
	s_waitcnt vmcnt(0)
	v_add_u32_e32 v16, v1, v0
	s_nop 2
	global_load_dword v2, v177, s[4:5] sc1
	v_readlane_b32 s4, v254, 40
	v_readlane_b32 s5, v254, 41
	s_waitcnt vmcnt(0)
	v_add_u32_e32 v16, v16, v2
	s_nop 2
	global_load_dword v3, v177, s[4:5] sc1
	v_readlane_b32 s4, v254, 42
	v_readlane_b32 s5, v254, 43
	s_waitcnt vmcnt(0)
	v_add_u32_e32 v16, v16, v3
	s_nop 2
	global_load_dword v4, v177, s[4:5] sc1
	v_readlane_b32 s4, v254, 44
	v_readlane_b32 s5, v254, 45
	s_waitcnt vmcnt(0)
	v_add_u32_e32 v16, v16, v4
	s_nop 2
	global_load_dword v5, v177, s[4:5] sc1
	v_readlane_b32 s4, v254, 46
	v_readlane_b32 s5, v254, 47
	s_waitcnt vmcnt(0)
	v_add_u32_e32 v16, v16, v5
	s_nop 2
	global_load_dword v6, v177, s[4:5] sc1
	v_readlane_b32 s4, v254, 48
	v_readlane_b32 s5, v254, 49
	s_waitcnt vmcnt(0)
	v_add_u32_e32 v16, v16, v6
	s_nop 2
	global_load_dword v7, v177, s[4:5] sc1
	v_readlane_b32 s4, v254, 50
	v_readlane_b32 s5, v254, 51
	s_waitcnt vmcnt(0)
	v_add_u32_e32 v16, v16, v7
	s_nop 2
	global_load_dword v8, v177, s[4:5] sc1
	v_readlane_b32 s4, v254, 52
	v_readlane_b32 s5, v254, 53
	s_waitcnt vmcnt(0)
	v_add_u32_e32 v16, v16, v8
	s_nop 2
	global_load_dword v9, v177, s[4:5] sc1
	v_readlane_b32 s4, v254, 54
	v_readlane_b32 s5, v254, 55
	s_waitcnt vmcnt(0)
	v_add_u32_e32 v16, v16, v9
	s_nop 2
	global_load_dword v10, v177, s[4:5] sc1
	v_readlane_b32 s4, v254, 56
	v_readlane_b32 s5, v254, 57
	s_waitcnt vmcnt(0)
	v_add_u32_e32 v16, v16, v10
	s_nop 2
	global_load_dword v11, v177, s[4:5] sc1
	v_readlane_b32 s4, v254, 58
	v_readlane_b32 s5, v254, 59
	s_waitcnt vmcnt(0)
	v_add_u32_e32 v16, v16, v11
	s_nop 2
	global_load_dword v12, v177, s[4:5] sc1
	v_readlane_b32 s4, v254, 60
	v_readlane_b32 s5, v254, 61
	s_waitcnt vmcnt(0)
	v_add_u32_e32 v16, v16, v12
	s_nop 2
	global_load_dword v13, v177, s[4:5] sc1
	v_readlane_b32 s4, v254, 62
	v_readlane_b32 s5, v254, 63
	s_waitcnt vmcnt(0)
	v_add_u32_e32 v16, v16, v13
	s_nop 2
	global_load_dword v14, v177, s[4:5] sc1
	v_readlane_b32 s4, v255, 0
	v_readlane_b32 s5, v255, 1
	s_waitcnt vmcnt(0)
	v_add_u32_e32 v16, v16, v14
	s_nop 2
	global_load_dword v15, v177, s[4:5] sc1
	s_mov_b64 s[4:5], -1
	s_waitcnt vmcnt(0)
	v_add_u32_e32 v16, v16, v15
	v_cmp_eq_u32_e32 vcc, s52, v16
	s_cbranch_vccnz .LBB0_275
	s_and_b32 s4, s11, 0xff
	s_cmp_eq_u32 s4, 0
	s_mov_b64 s[4:5], -1
	s_mov_b64 s[8:9], -1
	s_sleep 0
	s_cbranch_scc0 .LBB0_280
	v_readlane_b32 s4, v254, 32
	v_readlane_b32 s5, v254, 33
	s_nop 4
	global_load_dword v16, v177, s[4:5] sc1
	s_waitcnt vmcnt(0)
	v_cmp_eq_u32_e32 vcc, 0, v16
	s_cbranch_vccnz .LBB0_282
	s_mov_b64 s[8:9], 0
	s_mov_b64 s[4:5], -1

; DI unsigned xb_ld(unsigned* p)              { return __hip_atomic_load(p, __ATOMIC_RELAXED, __HIP_MEMORY_SCOPE_AGENT); }
; DI unsigned xb_add(unsigned* p, unsigned v) { return __hip_atomic_fetch_add(p, v, __ATOMIC_RELAXED, __HIP_MEMORY_SCOPE_AGENT); }
; #define XB_SPIN(cond, bar) do { unsigned _sp = 0; while (cond) { __builtin_amdgcn_s_sleep(1); \
;     if ((++_sp & 255u) == 0u) { if (xb_ld(&(bar)[XB_TMO])) break; if (_sp > XB_SPIN_CAP) { atomicAdd(&(bar)[XB_TMO], 1u); break; } } } } while (0)
; DI void xcd_barrier(unsigned* bar, volatile LAS unsigned* st, int wave) {
;     ...
;       else XB_SPIN(xb_ld(&bar[XB_TOPGEN]) == tg, bar);
;       __builtin_amdgcn_fence(__ATOMIC_ACQUIRE, "agent");
;       xb_add(&bar[XB_XGEN(x)], 1u);
;       asm volatile("s_waitcnt vmcnt(0)" ::: "memory");
;     } else {
;       XB_SPIN(xb_ld(&bar[XB_XGEN(x)]) == gen, bar);
.LBB0_294:
	s_and_b32 s13, s12, 0xff
	s_mov_b64 s[84:85], -1
	s_cmp_lg_u32 s13, 0
	s_mov_b64 s[36:37], -1
	s_sleep 0
	s_cbranch_scc1 .LBB0_297
	v_readlane_b32 s28, v254, 32
	v_readlane_b32 s29, v254, 33
	s_nop 4
	global_load_dword v0, v177, s[28:29] sc1
	s_waitcnt vmcnt(0)
	v_cmp_eq_u32_e32 vcc, 0, v0
	s_cbranch_vccnz .LBB0_299
	s_mov_b64 s[36:37], 0
	s_mov_b64 s[96:97], -1

; DI unsigned xb_ld(unsigned* p)              { return __hip_atomic_load(p, __ATOMIC_RELAXED, __HIP_MEMORY_SCOPE_AGENT); }
; DI unsigned xb_add(unsigned* p, unsigned v) { return __hip_atomic_fetch_add(p, v, __ATOMIC_RELAXED, __HIP_MEMORY_SCOPE_AGENT); }
; #define XB_SPIN(cond, bar) do { unsigned _sp = 0; while (cond) { __builtin_amdgcn_s_sleep(1); \
;     if ((++_sp & 255u) == 0u) { if (xb_ld(&(bar)[XB_TMO])) break; if (_sp > XB_SPIN_CAP) { atomicAdd(&(bar)[XB_TMO], 1u); break; } } } } while (0)
; DI void xcd_barrier(unsigned* bar, volatile LAS unsigned* st, int wave) {
;     ...
;       else XB_SPIN(xb_ld(&bar[XB_TOPGEN]) == tg, bar);
;       __builtin_amdgcn_fence(__ATOMIC_ACQUIRE, "agent");
;       xb_add(&bar[XB_XGEN(x)], 1u);
;       asm volatile("s_waitcnt vmcnt(0)" ::: "memory");
;     } else {
;       XB_SPIN(xb_ld(&bar[XB_XGEN(x)]) == gen, bar);
.LBB0_311:
	s_and_b32 s13, s12, 0xff
	s_mov_b64 s[78:79], -1
	s_cmp_lg_u32 s13, 0
	s_mov_b64 s[36:37], -1
	s_sleep 0
	s_cbranch_scc1 .LBB0_314
	v_readlane_b32 s28, v254, 32
	v_readlane_b32 s29, v254, 33
	s_nop 4
	global_load_dword v0, v177, s[28:29] sc1
	s_waitcnt vmcnt(0)
	v_cmp_eq_u32_e32 vcc, 0, v0
	s_cbranch_vccnz .LBB0_316
	s_mov_b64 s[36:37], 0
	s_mov_b64 s[84:85], -1
